# phase-1 census check: the 8 serialized sc1 counter loads issued together with one wait (on top of peel-zero in all GEMM loops)
# baseline (speedup 1.0000x reference)
.LBB0_151:
	s_nor_b64 s[4:5], s[6:7], s[2:3]
	s_and_b32 s2, s38, 7
	s_mov_b64 s[6:7], s[88:89]
	s_cmp_eq_u32 s2, 0
	s_load_dwordx2 s[2:3], s[6:7], 0xb8
	s_cselect_b64 s[8:9], -1, 0
	s_cmp_lt_u32 s54, 8
	s_cselect_b64 s[10:11], -1, 0
	s_and_b64 s[4:5], s[4:5], s[8:9]
	s_and_b64 s[8:9], s[4:5], s[10:11]
	s_and_saveexec_b64 s[4:5], s[8:9]
	s_cbranch_execz .LBB0_161
	v_mov_b32_e32 v0, 0x13763000
	v_mov_b32_e32 v1, 0x13764000
	s_waitcnt lgkmcnt(0)
	global_load_dword v2, v0, s[2:3] offset:3600 sc1
	global_load_dword v3, v0, s[2:3] offset:3856 sc1
	global_load_dword v4, v1, s[2:3] offset:16 sc1
	global_load_dword v5, v1, s[2:3] offset:272 sc1
	global_load_dword v6, v1, s[2:3] offset:528 sc1
	global_load_dword v7, v1, s[2:3] offset:784 sc1
	global_load_dword v8, v1, s[2:3] offset:1040 sc1
	global_load_dword v9, v1, s[2:3] offset:1296 sc1
	s_lshr_b32 s8, s38, 3
	s_waitcnt vmcnt(0)
	v_xor_b32_e32 v2, s8, v2
	v_xor_b32_e32 v3, s8, v3
	v_xor_b32_e32 v4, s8, v4
	v_xor_b32_e32 v5, s8, v5
	v_xor_b32_e32 v6, s8, v6
	v_xor_b32_e32 v7, s8, v7
	v_xor_b32_e32 v8, s8, v8
	v_xor_b32_e32 v9, s8, v9
	v_or3_b32 v2, v2, v3, v4
	v_or3_b32 v5, v5, v6, v7
	v_or3_b32 v8, v8, v9, v2
	v_or_b32_e32 v8, v8, v5
	v_cmp_ne_u32_e32 vcc, 0, v8
	s_cbranch_vccnz .LBB0_161
	s_add_i32 s8, 0, 0x20808
	v_mov_b32_e32 v0, s8
	ds_read_b32 v0, v0
	s_add_i32 s8, 0, 0x2080c
	v_mov_b32_e32 v1, s8
	s_waitcnt lgkmcnt(0)
	v_lshlrev_b32_e32 v0, 3, v0
	v_or_b32_e32 v0, s54, v0
	ds_write_b32 v1, v0
	v_mov_b32_e32 v0, 1
	v_mov_b32_e32 v1, 0x20810
	ds_write_b32 v1, v0
